# MLA QK chain: 8 fragment reads ahead of the dependent MFMA chain
# speedup vs baseline: 1.0540x; 1.0032x over previous
.LBB0_564:
	s_mul_hi_u32 s7, s4, 0xaaaaaaab
	s_lshr_b32 s7, s7, 1
	s_mul_i32 s7, s7, 0x9000
	v_subrev_u32_e32 v64, s7, v166
	v_add_u32_e32 v202, s36, v175
	v_add_u32_e32 v203, v202, v64
	v_subrev_u32_e32 v198, s7, v172
	v_add_u32_e32 v204, v202, v198
	v_subrev_u32_e32 v177, s7, v173
	v_add_u32_e32 v177, v202, v177
	v_subrev_u32_e32 v176, s7, v174
	v_add_u32_e32 v176, v202, v176
	ds_read_b128 v[64:67], v203 offset:12288
	ds_read_b128 v[198:201], v204 offset:12288
	ds_read_b128 v[232:235], v177 offset:12288
	ds_read_b128 v[236:239], v176 offset:12288
	ds_read_b128 v[240:243], v203 offset:12416
	ds_read_b128 v[244:247], v204 offset:12416
	ds_read_b128 v[248:251], v177 offset:12416
	ds_read_b128 v[252:255], v176 offset:12416
	s_waitcnt lgkmcnt(7)
	v_mfma_f32_32x32x16_bf16 v[64:79], v[64:67], v[142:145], 0
	s_waitcnt lgkmcnt(6)
	v_mfma_f32_32x32x16_bf16 v[64:79], v[198:201], v[138:141], v[64:79]
	ds_read_b128 v[198:201], v203 offset:12544
	s_waitcnt lgkmcnt(6)
	v_mfma_f32_32x32x16_bf16 v[64:79], v[232:235], v[134:137], v[64:79]
	ds_read_b128 v[232:235], v204 offset:12544
	s_waitcnt lgkmcnt(6)
	v_mfma_f32_32x32x16_bf16 v[64:79], v[236:239], v[130:133], v[64:79]
	ds_read_b128 v[236:239], v177 offset:12544
	s_waitcnt lgkmcnt(6)
	v_mfma_f32_32x32x16_bf16 v[64:79], v[240:243], v[126:129], v[64:79]
	ds_read_b128 v[240:243], v176 offset:12544
	v_max_f32_e32 v177, v80, v80
	v_max_f32_e32 v176, v81, v81
	v_max_f32_e32 v176, v177, v176
	v_max3_f32 v176, v176, v82, v83
	v_max3_f32 v176, v176, v84, v85
	v_max3_f32 v176, v176, v86, v87
	v_max3_f32 v176, v176, v88, v89
	s_waitcnt lgkmcnt(6)
	v_mfma_f32_32x32x16_bf16 v[64:79], v[244:247], v[122:125], v[64:79]
	s_waitcnt lgkmcnt(5)
	v_mfma_f32_32x32x16_bf16 v[64:79], v[248:251], v[118:121], v[64:79]
	s_waitcnt lgkmcnt(4)
	v_mfma_f32_32x32x16_bf16 v[64:79], v[252:255], v[114:117], v[64:79]
	s_waitcnt lgkmcnt(3)
	v_mfma_f32_32x32x16_bf16 v[64:79], v[198:201], v[110:113], v[64:79]
	s_waitcnt lgkmcnt(2)
	v_mfma_f32_32x32x16_bf16 v[64:79], v[232:235], v[106:109], v[64:79]
	s_waitcnt lgkmcnt(1)
	v_mfma_f32_32x32x16_bf16 v[64:79], v[236:239], v[102:105], v[64:79]
	s_waitcnt lgkmcnt(0)
	v_mfma_f32_32x32x16_bf16 v[64:79], v[240:243], v[98:101], v[64:79]
	v_max3_f32 v176, v176, v90, v91
	v_max3_f32 v176, v176, v92, v93
	v_max3_f32 v176, v176, v94, v95
	v_mov_b32_e32 v177, v176
	s_nop 1
	v_permlane32_swap_b32_e32 v176, v177
	v_max_f32_e32 v177, v177, v177
	v_max_f32_e32 v176, v176, v176
	v_max_f32_e32 v176, v176, v177
	v_add_f32_e32 v177, 0x41000000, v165
	v_cmp_gt_f32_e32 vcc, v176, v177
	s_cbranch_vccz .LBB0_566
	v_max_f32_e32 v176, v176, v176
	v_max_f32_e32 v177, v165, v165
	v_max_f32_e32 v177, v177, v176
	v_sub_f32_e32 v165, v165, v177
	v_exp_f32_e32 v176, v165
	v_mov_b32_e32 v165, v177
	v_pk_mul_f32 v[62:63], v[62:63], v[176:177] op_sel_hi:[1,0]
	v_pk_mul_f32 v[60:61], v[60:61], v[176:177] op_sel_hi:[1,0]
	v_pk_mul_f32 v[58:59], v[58:59], v[176:177] op_sel_hi:[1,0]
	v_pk_mul_f32 v[56:57], v[56:57], v[176:177] op_sel_hi:[1,0]
	v_pk_mul_f32 v[54:55], v[54:55], v[176:177] op_sel_hi:[1,0]
	v_pk_mul_f32 v[52:53], v[52:53], v[176:177] op_sel_hi:[1,0]
	v_pk_mul_f32 v[50:51], v[50:51], v[176:177] op_sel_hi:[1,0]
	v_pk_mul_f32 v[48:49], v[48:49], v[176:177] op_sel_hi:[1,0]
	v_pk_mul_f32 v[46:47], v[46:47], v[176:177] op_sel_hi:[1,0]
	v_pk_mul_f32 v[44:45], v[44:45], v[176:177] op_sel_hi:[1,0]
	v_pk_mul_f32 v[42:43], v[42:43], v[176:177] op_sel_hi:[1,0]
	v_pk_mul_f32 v[40:41], v[40:41], v[176:177] op_sel_hi:[1,0]
	v_pk_mul_f32 v[38:39], v[38:39], v[176:177] op_sel_hi:[1,0]
	v_pk_mul_f32 v[36:37], v[36:37], v[176:177] op_sel_hi:[1,0]
	v_pk_mul_f32 v[34:35], v[34:35], v[176:177] op_sel_hi:[1,0]
	v_pk_mul_f32 v[32:33], v[32:33], v[176:177] op_sel_hi:[1,0]
	v_pk_mul_f32 v[30:31], v[30:31], v[176:177] op_sel_hi:[1,0]
	v_pk_mul_f32 v[28:29], v[28:29], v[176:177] op_sel_hi:[1,0]
	v_pk_mul_f32 v[26:27], v[26:27], v[176:177] op_sel_hi:[1,0]
	v_pk_mul_f32 v[24:25], v[24:25], v[176:177] op_sel_hi:[1,0]
	v_pk_mul_f32 v[22:23], v[22:23], v[176:177] op_sel_hi:[1,0]
	v_pk_mul_f32 v[20:21], v[20:21], v[176:177] op_sel_hi:[1,0]
	v_pk_mul_f32 v[18:19], v[18:19], v[176:177] op_sel_hi:[1,0]
	v_pk_mul_f32 v[16:17], v[16:17], v[176:177] op_sel_hi:[1,0]
	v_pk_mul_f32 v[14:15], v[14:15], v[176:177] op_sel_hi:[1,0]
	v_pk_mul_f32 v[12:13], v[12:13], v[176:177] op_sel_hi:[1,0]
	v_pk_mul_f32 v[10:11], v[10:11], v[176:177] op_sel_hi:[1,0]
	v_pk_mul_f32 v[8:9], v[8:9], v[176:177] op_sel_hi:[1,0]
	v_pk_mul_f32 v[6:7], v[6:7], v[176:177] op_sel_hi:[1,0]
	v_pk_mul_f32 v[4:5], v[4:5], v[176:177] op_sel_hi:[1,0]
	v_pk_mul_f32 v[2:3], v[2:3], v[176:177] op_sel_hi:[1,0]
	v_pk_mul_f32 v[0:1], v[0:1], v[176:177] op_sel_hi:[1,0]
	v_mul_f32_e32 v164, v164, v176

.LBB0_584:
	s_mul_hi_u32 s8, s6, 0xaaaaaaab
	s_lshr_b32 s8, s8, 1
	s_mul_i32 s8, s8, 0x9000
	v_subrev_u32_e32 v64, s8, v201
	v_add_u32_e32 v215, s1, v208
	v_add_u32_e32 v216, v215, v64
	v_subrev_u32_e32 v210, s8, v205
	v_add_u32_e32 v217, v215, v210
	v_subrev_u32_e32 v214, s8, v206
	v_add_u32_e32 v214, v215, v214
	v_subrev_u32_e32 v209, s8, v207
	v_add_u32_e32 v209, v215, v209
	ds_read_b128 v[64:67], v216 offset:12288
	ds_read_b128 v[210:213], v217 offset:12288
	ds_read_b128 v[232:235], v214 offset:12288
	ds_read_b128 v[236:239], v209 offset:12288
	ds_read_b128 v[240:243], v216 offset:12416
	ds_read_b128 v[244:247], v217 offset:12416
	ds_read_b128 v[248:251], v214 offset:12416
	ds_read_b128 v[252:255], v209 offset:12416
	s_waitcnt lgkmcnt(7)
	v_mfma_f32_32x32x16_bf16 v[64:79], v[64:67], v[142:145], 0
	s_waitcnt lgkmcnt(6)
	v_mfma_f32_32x32x16_bf16 v[64:79], v[210:213], v[138:141], v[64:79]
	ds_read_b128 v[210:213], v216 offset:12544
	s_waitcnt lgkmcnt(6)
	v_mfma_f32_32x32x16_bf16 v[64:79], v[232:235], v[134:137], v[64:79]
	ds_read_b128 v[232:235], v217 offset:12544
	s_waitcnt lgkmcnt(6)
	v_mfma_f32_32x32x16_bf16 v[64:79], v[236:239], v[130:133], v[64:79]
	ds_read_b128 v[236:239], v214 offset:12544
	s_waitcnt lgkmcnt(6)
	v_mfma_f32_32x32x16_bf16 v[64:79], v[240:243], v[126:129], v[64:79]
	ds_read_b128 v[240:243], v209 offset:12544
	v_max_f32_e32 v209, v81, v81
	s_waitcnt lgkmcnt(6)
	v_mfma_f32_32x32x16_bf16 v[64:79], v[244:247], v[122:125], v[64:79]
	s_waitcnt lgkmcnt(5)
	v_mfma_f32_32x32x16_bf16 v[64:79], v[248:251], v[118:121], v[64:79]
	s_waitcnt lgkmcnt(4)
	v_mfma_f32_32x32x16_bf16 v[64:79], v[252:255], v[114:117], v[64:79]
	s_waitcnt lgkmcnt(3)
	v_mfma_f32_32x32x16_bf16 v[64:79], v[210:213], v[110:113], v[64:79]
	s_waitcnt lgkmcnt(2)
	v_mfma_f32_32x32x16_bf16 v[64:79], v[232:235], v[106:109], v[64:79]
	s_waitcnt lgkmcnt(1)
	v_mfma_f32_32x32x16_bf16 v[64:79], v[236:239], v[102:105], v[64:79]
	s_waitcnt lgkmcnt(0)
	v_mfma_f32_32x32x16_bf16 v[64:79], v[240:243], v[98:101], v[64:79]
	v_max_f32_e32 v210, v80, v80
	v_max_f32_e32 v209, v210, v209
	v_max3_f32 v209, v209, v82, v83
	v_max3_f32 v209, v209, v84, v85
	v_max3_f32 v209, v209, v86, v87
	v_max3_f32 v209, v209, v88, v89
	v_max3_f32 v209, v209, v90, v91
	v_max3_f32 v209, v209, v92, v93
	v_max3_f32 v209, v209, v94, v95
	v_mov_b32_e32 v210, v209
	s_nop 1
	v_permlane32_swap_b32_e32 v209, v210
	v_max_f32_e32 v210, v210, v210
	v_max_f32_e32 v209, v209, v209
	v_max_f32_e32 v209, v209, v210
	v_add_f32_e32 v210, 0x41000000, v198
	v_cmp_gt_f32_e32 vcc, v209, v210
	s_cbranch_vccz .LBB0_586
	v_max_f32_e32 v209, v209, v209
	v_max_f32_e32 v210, v198, v198
	v_max_f32_e32 v209, v210, v209
	v_sub_f32_e32 v198, v198, v209
	v_exp_f32_e32 v198, v198
	s_nop 0
	v_pk_mul_f32 v[62:63], v[62:63], v[198:199] op_sel_hi:[1,0]
	v_pk_mul_f32 v[60:61], v[60:61], v[198:199] op_sel_hi:[1,0]
	v_pk_mul_f32 v[58:59], v[58:59], v[198:199] op_sel_hi:[1,0]
	v_pk_mul_f32 v[56:57], v[56:57], v[198:199] op_sel_hi:[1,0]
	v_pk_mul_f32 v[54:55], v[54:55], v[198:199] op_sel_hi:[1,0]
	v_pk_mul_f32 v[52:53], v[52:53], v[198:199] op_sel_hi:[1,0]
	v_pk_mul_f32 v[50:51], v[50:51], v[198:199] op_sel_hi:[1,0]
	v_pk_mul_f32 v[48:49], v[48:49], v[198:199] op_sel_hi:[1,0]
	v_pk_mul_f32 v[46:47], v[46:47], v[198:199] op_sel_hi:[1,0]
	v_pk_mul_f32 v[44:45], v[44:45], v[198:199] op_sel_hi:[1,0]
	v_pk_mul_f32 v[42:43], v[42:43], v[198:199] op_sel_hi:[1,0]
	v_pk_mul_f32 v[40:41], v[40:41], v[198:199] op_sel_hi:[1,0]
	v_pk_mul_f32 v[38:39], v[38:39], v[198:199] op_sel_hi:[1,0]
	v_pk_mul_f32 v[36:37], v[36:37], v[198:199] op_sel_hi:[1,0]
	v_pk_mul_f32 v[34:35], v[34:35], v[198:199] op_sel_hi:[1,0]
	v_pk_mul_f32 v[32:33], v[32:33], v[198:199] op_sel_hi:[1,0]
	v_pk_mul_f32 v[30:31], v[30:31], v[198:199] op_sel_hi:[1,0]
	v_pk_mul_f32 v[28:29], v[28:29], v[198:199] op_sel_hi:[1,0]
	v_pk_mul_f32 v[26:27], v[26:27], v[198:199] op_sel_hi:[1,0]
	v_pk_mul_f32 v[24:25], v[24:25], v[198:199] op_sel_hi:[1,0]
	v_pk_mul_f32 v[22:23], v[22:23], v[198:199] op_sel_hi:[1,0]
	v_pk_mul_f32 v[20:21], v[20:21], v[198:199] op_sel_hi:[1,0]
	v_pk_mul_f32 v[18:19], v[18:19], v[198:199] op_sel_hi:[1,0]
	v_pk_mul_f32 v[16:17], v[16:17], v[198:199] op_sel_hi:[1,0]
	v_pk_mul_f32 v[14:15], v[14:15], v[198:199] op_sel_hi:[1,0]
	v_pk_mul_f32 v[12:13], v[12:13], v[198:199] op_sel_hi:[1,0]
	v_pk_mul_f32 v[10:11], v[10:11], v[198:199] op_sel_hi:[1,0]
	v_pk_mul_f32 v[8:9], v[8:9], v[198:199] op_sel_hi:[1,0]
	v_pk_mul_f32 v[6:7], v[6:7], v[198:199] op_sel_hi:[1,0]
	v_pk_mul_f32 v[4:5], v[4:5], v[198:199] op_sel_hi:[1,0]
	v_pk_mul_f32 v[2:3], v[2:3], v[198:199] op_sel_hi:[1,0]
	v_pk_mul_f32 v[0:1], v[0:1], v[198:199] op_sel_hi:[1,0]
	v_mul_f32_e32 v177, v177, v198
	v_mov_b32_e32 v198, v209

.LBB0_611:
	s_mul_hi_u32 s6, s0, 0xaaaaaaab
	s_lshr_b32 s6, s6, 1
	s_mul_i32 s6, s6, 0x9000
	v_subrev_u32_e32 v64, s6, v201
	v_add_u32_e32 v216, s4, v209
	v_add_u32_e32 v217, v216, v64
	v_subrev_u32_e32 v210, s6, v206
	v_add_u32_e32 v218, v216, v210
	v_subrev_u32_e32 v215, s6, v207
	v_add_u32_e32 v215, v216, v215
	v_subrev_u32_e32 v214, s6, v208
	v_add_u32_e32 v214, v216, v214
	ds_read_b128 v[64:67], v217 offset:12288
	ds_read_b128 v[210:213], v218 offset:12288
	ds_read_b128 v[232:235], v215 offset:12288
	ds_read_b128 v[236:239], v214 offset:12288
	ds_read_b128 v[240:243], v217 offset:12416
	ds_read_b128 v[244:247], v218 offset:12416
	ds_read_b128 v[248:251], v215 offset:12416
	ds_read_b128 v[252:255], v214 offset:12416
	s_waitcnt lgkmcnt(7)
	v_mfma_f32_32x32x16_bf16 v[64:79], v[64:67], v[142:145], 0
	s_waitcnt lgkmcnt(6)
	v_mfma_f32_32x32x16_bf16 v[64:79], v[210:213], v[138:141], v[64:79]
	ds_read_b128 v[210:213], v217 offset:12544
	s_waitcnt lgkmcnt(6)
	v_mfma_f32_32x32x16_bf16 v[64:79], v[232:235], v[134:137], v[64:79]
	ds_read_b128 v[232:235], v218 offset:12544
	s_waitcnt lgkmcnt(6)
	v_mfma_f32_32x32x16_bf16 v[64:79], v[236:239], v[130:133], v[64:79]
	ds_read_b128 v[236:239], v215 offset:12544
	s_waitcnt lgkmcnt(6)
	v_mfma_f32_32x32x16_bf16 v[64:79], v[240:243], v[126:129], v[64:79]
	ds_read_b128 v[240:243], v214 offset:12544
	s_waitcnt lgkmcnt(6)
	v_mfma_f32_32x32x16_bf16 v[64:79], v[244:247], v[122:125], v[64:79]
	s_waitcnt lgkmcnt(5)
	v_mfma_f32_32x32x16_bf16 v[64:79], v[248:251], v[118:121], v[64:79]
	s_waitcnt lgkmcnt(4)
	v_mfma_f32_32x32x16_bf16 v[64:79], v[252:255], v[114:117], v[64:79]
	s_waitcnt lgkmcnt(3)
	v_mfma_f32_32x32x16_bf16 v[64:79], v[210:213], v[110:113], v[64:79]
	s_waitcnt lgkmcnt(2)
	v_mfma_f32_32x32x16_bf16 v[64:79], v[232:235], v[106:109], v[64:79]
	s_waitcnt lgkmcnt(1)
	v_mfma_f32_32x32x16_bf16 v[64:79], v[236:239], v[102:105], v[64:79]
	s_waitcnt lgkmcnt(0)
	v_mfma_f32_32x32x16_bf16 v[64:79], v[240:243], v[98:101], v[64:79]
	v_max_f32_e32 v210, v81, v81
	v_max_f32_e32 v211, v80, v80
	v_max_f32_e32 v210, v211, v210
	v_max3_f32 v210, v210, v82, v83
	v_max3_f32 v210, v210, v84, v85
	v_max3_f32 v210, v210, v86, v87
	v_max3_f32 v210, v210, v88, v89
	v_max3_f32 v210, v210, v90, v91
	v_max3_f32 v210, v210, v92, v93
	v_max3_f32 v210, v210, v94, v95
	v_mov_b32_e32 v211, v210
	s_nop 1
	v_permlane32_swap_b32_e32 v210, v211
	v_max_f32_e32 v211, v211, v211
	v_max_f32_e32 v210, v210, v210
	v_max_f32_e32 v210, v210, v211
	v_add_f32_e32 v211, 0x41000000, v198
	v_cmp_gt_f32_e32 vcc, v210, v211
	s_cbranch_vccz .LBB0_613
	v_max_f32_e32 v210, v210, v210
	v_max_f32_e32 v211, v198, v198
	v_max_f32_e32 v210, v211, v210
	v_sub_f32_e32 v198, v198, v210
	v_exp_f32_e32 v198, v198
	s_nop 0
	v_pk_mul_f32 v[62:63], v[62:63], v[198:199] op_sel_hi:[1,0]
	v_pk_mul_f32 v[60:61], v[60:61], v[198:199] op_sel_hi:[1,0]
	v_pk_mul_f32 v[58:59], v[58:59], v[198:199] op_sel_hi:[1,0]
	v_pk_mul_f32 v[56:57], v[56:57], v[198:199] op_sel_hi:[1,0]
	v_pk_mul_f32 v[54:55], v[54:55], v[198:199] op_sel_hi:[1,0]
	v_pk_mul_f32 v[52:53], v[52:53], v[198:199] op_sel_hi:[1,0]
	v_pk_mul_f32 v[50:51], v[50:51], v[198:199] op_sel_hi:[1,0]
	v_pk_mul_f32 v[48:49], v[48:49], v[198:199] op_sel_hi:[1,0]
	v_pk_mul_f32 v[46:47], v[46:47], v[198:199] op_sel_hi:[1,0]
	v_pk_mul_f32 v[44:45], v[44:45], v[198:199] op_sel_hi:[1,0]
	v_pk_mul_f32 v[42:43], v[42:43], v[198:199] op_sel_hi:[1,0]
	v_pk_mul_f32 v[40:41], v[40:41], v[198:199] op_sel_hi:[1,0]
	v_pk_mul_f32 v[38:39], v[38:39], v[198:199] op_sel_hi:[1,0]
	v_pk_mul_f32 v[36:37], v[36:37], v[198:199] op_sel_hi:[1,0]
	v_pk_mul_f32 v[34:35], v[34:35], v[198:199] op_sel_hi:[1,0]
	v_pk_mul_f32 v[32:33], v[32:33], v[198:199] op_sel_hi:[1,0]
	v_pk_mul_f32 v[30:31], v[30:31], v[198:199] op_sel_hi:[1,0]
	v_pk_mul_f32 v[28:29], v[28:29], v[198:199] op_sel_hi:[1,0]
	v_pk_mul_f32 v[26:27], v[26:27], v[198:199] op_sel_hi:[1,0]
	v_pk_mul_f32 v[24:25], v[24:25], v[198:199] op_sel_hi:[1,0]
	v_pk_mul_f32 v[22:23], v[22:23], v[198:199] op_sel_hi:[1,0]
	v_pk_mul_f32 v[20:21], v[20:21], v[198:199] op_sel_hi:[1,0]
	v_pk_mul_f32 v[18:19], v[18:19], v[198:199] op_sel_hi:[1,0]
	v_pk_mul_f32 v[16:17], v[16:17], v[198:199] op_sel_hi:[1,0]
	v_pk_mul_f32 v[14:15], v[14:15], v[198:199] op_sel_hi:[1,0]
	v_pk_mul_f32 v[12:13], v[12:13], v[198:199] op_sel_hi:[1,0]
	v_pk_mul_f32 v[10:11], v[10:11], v[198:199] op_sel_hi:[1,0]
	v_pk_mul_f32 v[8:9], v[8:9], v[198:199] op_sel_hi:[1,0]
	v_pk_mul_f32 v[6:7], v[6:7], v[198:199] op_sel_hi:[1,0]
	v_pk_mul_f32 v[4:5], v[4:5], v[198:199] op_sel_hi:[1,0]
	v_pk_mul_f32 v[2:3], v[2:3], v[198:199] op_sel_hi:[1,0]
	v_pk_mul_f32 v[0:1], v[0:1], v[198:199] op_sel_hi:[1,0]
	v_mul_f32_e32 v177, v177, v198
	v_mov_b32_e32 v198, v210
